# epilogue-before-last-barrier for the lagging wave half also in the FFN-down and attention-out GEMMs
# speedup vs baseline: 1.0173x; 1.0021x over previous
.LBB0_1090:
	s_mov_b32 s50, 0
	v_readlane_b32 s0, v251, 36
	s_waitcnt lgkmcnt(0)
	v_readlane_b32 s26, v255, 49
	s_cmp_eq_u32 s26, 0
	s_cselect_b32 s26, s91, s26
	v_readlane_b32 s14, v252, 47
	s_waitcnt vmcnt(0)
	v_lshl_add_u32 v0, s0, 6, v220
	s_movk_i32 s0, 0x100
	s_cmp_lt_u32 s26, 0x100
	s_cbranch_scc1 .Loute_n
	s_add_i32 s0, s26, 1

.LBB0_1104:
	s_cmp_eq_u32 s50, 0
	s_cbranch_scc1 .Lepib_out_nb
	s_mov_b32 s50, 0
	s_barrier

.LBB0_1117:
	s_add_i32 s41, s22, 2
	s_add_u32 s20, s14, 0x100
	s_addc_u32 s21, s15, 0
	s_add_i32 s42, 0, 0x10000
	s_waitcnt vmcnt(0)
	v_add_u32_e32 v102, s42, v230
	ds_read_b128 v[78:81], v102
	ds_read_b128 v[94:97], v102 offset:2048
	ds_read_b128 v[86:89], v102 offset:1024
	ds_read_b128 v[102:105], v102 offset:3072
	s_cmp_eq_u32 s38, s22
	s_cselect_b32 s22, s18, s39
	s_cselect_b32 s25, s17, s21
	s_cselect_b32 s24, s16, s20
	s_cselect_b32 s23, s19, s40
	v_lshl_add_u64 v[178:179], s[14:15], 0, v[200:201]
	s_add_i32 m0, s28, 0xc000
	ds_read_b128 v[122:125], v232
	ds_read_b128 v[130:133], v232 offset:2048
	ds_read_b128 v[154:157], v232 offset:4096
	ds_read_b128 v[170:173], v232 offset:6144
	ds_read_b128 v[126:129], v232 offset:1024
	ds_read_b128 v[134:137], v232 offset:3072
	ds_read_b128 v[158:161], v232 offset:5120
	ds_read_b128 v[174:177], v232 offset:7168
	global_load_lds_dwordx4 v[178:179], off
	v_lshl_add_u64 v[178:179], s[14:15], 0, v[202:203]
	s_add_i32 m0, s28, 0xe000
	s_nop 0
	global_load_lds_dwordx4 v[178:179], off
	s_waitcnt lgkmcnt(8)
	s_barrier
	s_waitcnt lgkmcnt(7)
	s_setprio 1
	v_mfma_f32_16x16x32_f16 v[166:169], v[78:81], v[122:125], v[166:169]
	v_mfma_f32_16x16x32_f16 v[162:165], v[94:97], v[122:125], v[162:165]
	s_waitcnt lgkmcnt(6)
	v_mfma_f32_16x16x32_f16 v[150:153], v[78:81], v[130:133], v[150:153]
	v_mfma_f32_16x16x32_f16 v[142:145], v[94:97], v[130:133], v[142:145]
	s_waitcnt lgkmcnt(5)
	v_mfma_f32_16x16x32_f16 v[110:113], v[78:81], v[154:157], v[110:113]
	v_mfma_f32_16x16x32_f16 v[106:109], v[94:97], v[154:157], v[106:109]
	s_waitcnt lgkmcnt(4)
	v_mfma_f32_16x16x32_f16 v[82:85], v[78:81], v[170:173], v[82:85]
	v_mfma_f32_16x16x32_f16 v[74:77], v[94:97], v[170:173], v[74:77]
	s_waitcnt lgkmcnt(3)
	v_mfma_f32_16x16x32_f16 v[166:169], v[86:89], v[126:129], v[166:169]
	v_mfma_f32_16x16x32_f16 v[162:165], v[102:105], v[126:129], v[162:165]
	s_waitcnt lgkmcnt(2)
	v_mfma_f32_16x16x32_f16 v[150:153], v[86:89], v[134:137], v[150:153]
	v_mfma_f32_16x16x32_f16 v[142:145], v[102:105], v[134:137], v[142:145]
	s_waitcnt lgkmcnt(1)
	v_mfma_f32_16x16x32_f16 v[110:113], v[86:89], v[158:161], v[110:113]
	v_mfma_f32_16x16x32_f16 v[106:109], v[102:105], v[158:161], v[106:109]
	s_waitcnt lgkmcnt(0)
	v_mfma_f32_16x16x32_f16 v[82:85], v[86:89], v[174:177], v[82:85]
	v_mfma_f32_16x16x32_f16 v[74:77], v[102:105], v[174:177], v[74:77]
	s_setprio 0
	s_barrier
	s_add_i32 s43, 0, 0x14000
	s_add_i32 s14, s42, s13
	v_add_u32_e32 v190, s43, v230
	v_lshl_add_u64 v[204:205], s[22:23], 0, v[32:33]
	s_mov_b32 m0, s14
	ds_read_b128 v[178:181], v190
	ds_read_b128 v[186:189], v190 offset:2048
	ds_read_b128 v[182:185], v190 offset:1024
	ds_read_b128 v[190:193], v190 offset:3072
	global_load_lds_dwordx4 v[204:205], off
	v_lshl_add_u64 v[206:207], s[22:23], 0, v[198:199]
	s_add_i32 m0, s14, 0x2000
	s_nop 0
	global_load_lds_dwordx4 v[206:207], off
	s_barrier
	s_waitcnt lgkmcnt(3)
	s_setprio 1
	v_mfma_f32_16x16x32_f16 v[146:149], v[178:181], v[122:125], v[146:149]
	v_mfma_f32_16x16x32_f16 v[118:121], v[178:181], v[130:133], v[118:121]
	s_waitcnt lgkmcnt(2)
	v_mfma_f32_16x16x32_f16 v[114:117], v[186:189], v[130:133], v[114:117]
	v_mfma_f32_16x16x32_f16 v[98:101], v[178:181], v[154:157], v[98:101]
	v_mfma_f32_16x16x32_f16 v[90:93], v[186:189], v[154:157], v[90:93]
	v_mfma_f32_16x16x32_f16 v[70:73], v[178:181], v[170:173], v[70:73]
	s_waitcnt lgkmcnt(1)
	v_mfma_f32_16x16x32_f16 v[66:69], v[186:189], v[170:173], v[66:69]
	v_mfma_f32_16x16x32_f16 v[146:149], v[182:185], v[126:129], v[146:149]
	v_mfma_f32_16x16x32_f16 v[122:125], v[186:189], v[122:125], v[138:141]
	v_mfma_f32_16x16x32_f16 v[118:121], v[182:185], v[134:137], v[118:121]
	s_waitcnt lgkmcnt(0)
	v_mfma_f32_16x16x32_f16 v[114:117], v[190:193], v[134:137], v[114:117]
	v_mfma_f32_16x16x32_f16 v[98:101], v[182:185], v[158:161], v[98:101]
	v_mfma_f32_16x16x32_f16 v[90:93], v[190:193], v[158:161], v[90:93]
	v_mfma_f32_16x16x32_f16 v[70:73], v[182:185], v[174:177], v[70:73]
	v_mfma_f32_16x16x32_f16 v[66:69], v[190:193], v[174:177], v[66:69]
	v_mfma_f32_16x16x32_f16 v[122:125], v[190:193], v[126:129], v[122:125]
	s_setprio 0
	s_mov_b32 m0, s28
	v_lshl_add_u64 v[208:209], s[24:25], 0, v[32:33]
	s_barrier
	ds_read_b128 v[126:129], v232 offset:16384
	ds_read_b128 v[134:137], v232 offset:18432
	ds_read_b128 v[154:157], v232 offset:20480
	ds_read_b128 v[170:173], v232 offset:22528
	ds_read_b128 v[130:133], v232 offset:17408
	ds_read_b128 v[138:141], v232 offset:19456
	ds_read_b128 v[158:161], v232 offset:21504
	ds_read_b128 v[174:177], v232 offset:23552
	global_load_lds_dwordx4 v[208:209], off
	v_lshl_add_u64 v[210:211], s[24:25], 0, v[198:199]
	s_mov_b32 m0, s29
	s_nop 0
	global_load_lds_dwordx4 v[210:211], off
	s_barrier
	s_waitcnt lgkmcnt(7)
	s_setprio 1
	v_mfma_f32_16x16x32_f16 v[62:65], v[78:81], v[126:129], v[62:65]
	v_mfma_f32_16x16x32_f16 v[58:61], v[94:97], v[126:129], v[58:61]
	s_waitcnt lgkmcnt(6)
	v_mfma_f32_16x16x32_f16 v[46:49], v[78:81], v[134:137], v[46:49]
	v_mfma_f32_16x16x32_f16 v[42:45], v[94:97], v[134:137], v[42:45]
	s_waitcnt lgkmcnt(5)
	v_mfma_f32_16x16x32_f16 v[28:31], v[78:81], v[154:157], v[28:31]
	v_mfma_f32_16x16x32_f16 v[24:27], v[94:97], v[154:157], v[24:27]
	s_waitcnt lgkmcnt(4)
	v_mfma_f32_16x16x32_f16 v[12:15], v[78:81], v[170:173], v[12:15]
	v_mfma_f32_16x16x32_f16 v[8:11], v[94:97], v[170:173], v[8:11]
	s_waitcnt lgkmcnt(3)
	v_mfma_f32_16x16x32_f16 v[62:65], v[86:89], v[130:133], v[62:65]
	v_mfma_f32_16x16x32_f16 v[58:61], v[102:105], v[130:133], v[58:61]
	s_waitcnt lgkmcnt(2)
	v_mfma_f32_16x16x32_f16 v[46:49], v[86:89], v[138:141], v[46:49]
	v_mfma_f32_16x16x32_f16 v[42:45], v[102:105], v[138:141], v[42:45]
	s_waitcnt lgkmcnt(1)
	v_mfma_f32_16x16x32_f16 v[28:31], v[86:89], v[158:161], v[28:31]
	v_mfma_f32_16x16x32_f16 v[24:27], v[102:105], v[158:161], v[24:27]
	s_waitcnt lgkmcnt(0)
	v_mfma_f32_16x16x32_f16 v[12:15], v[86:89], v[174:177], v[12:15]
	v_mfma_f32_16x16x32_f16 v[8:11], v[102:105], v[174:177], v[8:11]
	s_setprio 0
	s_barrier
	s_add_u32 s14, s22, 0x40000
	s_addc_u32 s15, s23, 0
	s_add_i32 s42, s43, s13
	v_lshl_add_u64 v[78:79], s[14:15], 0, v[32:33]
	s_mov_b32 m0, s42
	s_nop 0
	global_load_lds_dwordx4 v[78:79], off
	v_lshl_add_u64 v[78:79], s[14:15], 0, v[198:199]
	s_add_i32 m0, s42, 0x2000
	s_nop 0
	global_load_lds_dwordx4 v[78:79], off
	s_waitcnt vmcnt(6)
	s_barrier
	s_setprio 1
	v_mfma_f32_16x16x32_f16 v[54:57], v[178:181], v[126:129], v[54:57]
	v_mfma_f32_16x16x32_f16 v[50:53], v[186:189], v[126:129], v[50:53]
	v_mfma_f32_16x16x32_f16 v[38:41], v[178:181], v[134:137], v[38:41]
	v_mfma_f32_16x16x32_f16 v[34:37], v[186:189], v[134:137], v[34:37]
	v_mfma_f32_16x16x32_f16 v[20:23], v[178:181], v[154:157], v[20:23]
	v_mfma_f32_16x16x32_f16 v[16:19], v[186:189], v[154:157], v[16:19]
	v_mfma_f32_16x16x32_f16 v[4:7], v[178:181], v[170:173], v[4:7]
	v_mfma_f32_16x16x32_f16 v[0:3], v[186:189], v[170:173], v[0:3]
	v_mfma_f32_16x16x32_f16 v[54:57], v[182:185], v[130:133], v[54:57]
	v_mfma_f32_16x16x32_f16 v[50:53], v[190:193], v[130:133], v[50:53]
	v_mfma_f32_16x16x32_f16 v[38:41], v[182:185], v[138:141], v[38:41]
	v_mfma_f32_16x16x32_f16 v[34:37], v[190:193], v[138:141], v[34:37]
	v_mfma_f32_16x16x32_f16 v[20:23], v[182:185], v[158:161], v[20:23]
	v_mfma_f32_16x16x32_f16 v[16:19], v[190:193], v[158:161], v[16:19]
	v_mfma_f32_16x16x32_f16 v[4:7], v[182:185], v[174:177], v[4:7]
	v_mfma_f32_16x16x32_f16 v[0:3], v[190:193], v[174:177], v[0:3]
	s_setprio 0
	s_add_i32 s42, 0, 0x18000
	v_add_u32_e32 v102, s42, v230
	s_barrier
	ds_read_b128 v[78:81], v102
	ds_read_b128 v[86:89], v102 offset:1024
	ds_read_b128 v[94:97], v102 offset:2048
	ds_read_b128 v[102:105], v102 offset:3072
	s_add_u32 s14, s24, 0x40000
	s_addc_u32 s15, s25, 0
	s_mov_b32 m0, s30
	v_lshl_add_u64 v[138:139], s[14:15], 0, v[32:33]
	ds_read_b128 v[126:129], v232 offset:32768
	ds_read_b128 v[130:133], v232 offset:33792
	ds_read_b128 v[134:137], v232 offset:34816
	ds_read_b128 v[154:157], v232 offset:35840
	ds_read_b128 v[158:161], v232 offset:36864
	ds_read_b128 v[174:177], v232 offset:38912
	ds_read_b128 v[170:173], v232 offset:37888
	ds_read_b128 v[178:181], v232 offset:39936
	global_load_lds_dwordx4 v[138:139], off
	v_lshl_add_u64 v[138:139], s[14:15], 0, v[198:199]
	s_mov_b32 m0, s31
	s_nop 0
	global_load_lds_dwordx4 v[138:139], off
	s_waitcnt lgkmcnt(8)
	s_barrier
	s_waitcnt lgkmcnt(6)
	s_setprio 1
	v_mfma_f32_16x16x32_f16 v[138:141], v[78:81], v[126:129], v[166:169]
	v_mfma_f32_16x16x32_f16 v[166:169], v[86:89], v[130:133], v[138:141]
	v_mfma_f32_16x16x32_f16 v[138:141], v[94:97], v[126:129], v[162:165]
	v_mfma_f32_16x16x32_f16 v[162:165], v[102:105], v[130:133], v[138:141]
	s_waitcnt lgkmcnt(4)
	v_mfma_f32_16x16x32_f16 v[138:141], v[78:81], v[134:137], v[150:153]
	v_mfma_f32_16x16x32_f16 v[150:153], v[86:89], v[154:157], v[138:141]
	s_waitcnt lgkmcnt(3)
	v_mfma_f32_16x16x32_f16 v[138:141], v[94:97], v[134:137], v[142:145]
	v_mfma_f32_16x16x32_f16 v[110:113], v[78:81], v[158:161], v[110:113]
	s_waitcnt lgkmcnt(2)
	v_mfma_f32_16x16x32_f16 v[106:109], v[94:97], v[158:161], v[106:109]
	v_mfma_f32_16x16x32_f16 v[82:85], v[78:81], v[174:177], v[82:85]
	v_mfma_f32_16x16x32_f16 v[74:77], v[94:97], v[174:177], v[74:77]
	v_mfma_f32_16x16x32_f16 v[142:145], v[102:105], v[154:157], v[138:141]
	s_waitcnt lgkmcnt(1)
	v_mfma_f32_16x16x32_f16 v[110:113], v[86:89], v[170:173], v[110:113]
	v_mfma_f32_16x16x32_f16 v[106:109], v[102:105], v[170:173], v[106:109]
	s_waitcnt lgkmcnt(0)
	v_mfma_f32_16x16x32_f16 v[82:85], v[86:89], v[178:181], v[82:85]
	v_mfma_f32_16x16x32_f16 v[74:77], v[102:105], v[178:181], v[74:77]
	s_setprio 0
	s_barrier
	s_add_i32 s24, 0, 0x1c000
	v_add_u32_e32 v138, s24, v230
	s_add_i32 s14, s42, s13
	ds_read_b128 v[182:185], v138
	ds_read_b128 v[190:193], v138 offset:2048
	ds_read_b128 v[186:189], v138 offset:1024
	ds_read_b128 v[194:197], v138 offset:3072
	v_lshl_add_u64 v[138:139], v[204:205], 0, s[84:85]
	s_mov_b32 m0, s14
	s_nop 0
	global_load_lds_dwordx4 v[138:139], off
	v_lshl_add_u64 v[138:139], v[206:207], 0, s[84:85]
	s_add_i32 m0, s14, 0x2000
	s_nop 0
	global_load_lds_dwordx4 v[138:139], off
	s_barrier
	s_waitcnt lgkmcnt(2)
	s_setprio 1
	v_mfma_f32_16x16x32_f16 v[138:141], v[182:185], v[126:129], v[146:149]
	v_mfma_f32_16x16x32_f16 v[122:125], v[190:193], v[126:129], v[122:125]
	v_mfma_f32_16x16x32_f16 v[118:121], v[182:185], v[134:137], v[118:121]
	v_mfma_f32_16x16x32_f16 v[114:117], v[190:193], v[134:137], v[114:117]
	v_mfma_f32_16x16x32_f16 v[98:101], v[182:185], v[158:161], v[98:101]
	v_mfma_f32_16x16x32_f16 v[90:93], v[190:193], v[158:161], v[90:93]
	v_mfma_f32_16x16x32_f16 v[70:73], v[182:185], v[174:177], v[70:73]
	v_mfma_f32_16x16x32_f16 v[66:69], v[190:193], v[174:177], v[66:69]
	s_waitcnt lgkmcnt(0)
	v_mfma_f32_16x16x32_f16 v[146:149], v[186:189], v[130:133], v[138:141]
	v_mfma_f32_16x16x32_f16 v[138:141], v[194:197], v[130:133], v[122:125]
	v_mfma_f32_16x16x32_f16 v[118:121], v[186:189], v[154:157], v[118:121]
	v_mfma_f32_16x16x32_f16 v[114:117], v[194:197], v[154:157], v[114:117]
	v_mfma_f32_16x16x32_f16 v[98:101], v[186:189], v[170:173], v[98:101]
	v_mfma_f32_16x16x32_f16 v[90:93], v[194:197], v[170:173], v[90:93]
	v_mfma_f32_16x16x32_f16 v[70:73], v[186:189], v[178:181], v[70:73]
	v_mfma_f32_16x16x32_f16 v[66:69], v[194:197], v[178:181], v[66:69]
	s_setprio 0
	s_mov_b32 m0, s34
	v_lshl_add_u64 v[178:179], v[208:209], 0, s[84:85]
	s_barrier
	ds_read_b128 v[122:125], v232 offset:49152
	ds_read_b128 v[130:133], v232 offset:51200
	ds_read_b128 v[154:157], v232 offset:53248
	ds_read_b128 v[170:173], v232 offset:55296
	ds_read_b128 v[126:129], v232 offset:50176
	ds_read_b128 v[134:137], v232 offset:52224
	ds_read_b128 v[158:161], v232 offset:54272
	ds_read_b128 v[174:177], v232 offset:56320
	global_load_lds_dwordx4 v[178:179], off
	v_lshl_add_u64 v[178:179], v[210:211], 0, s[84:85]
	s_mov_b32 m0, s35
	s_nop 0
	global_load_lds_dwordx4 v[178:179], off
	s_barrier
	s_waitcnt lgkmcnt(7)
	s_setprio 1
	v_mfma_f32_16x16x32_f16 v[62:65], v[78:81], v[122:125], v[62:65]
	v_mfma_f32_16x16x32_f16 v[58:61], v[94:97], v[122:125], v[58:61]
	s_waitcnt lgkmcnt(6)
	v_mfma_f32_16x16x32_f16 v[46:49], v[78:81], v[130:133], v[46:49]
	v_mfma_f32_16x16x32_f16 v[42:45], v[94:97], v[130:133], v[42:45]
	s_waitcnt lgkmcnt(5)
	v_mfma_f32_16x16x32_f16 v[28:31], v[78:81], v[154:157], v[28:31]
	v_mfma_f32_16x16x32_f16 v[24:27], v[94:97], v[154:157], v[24:27]
	s_waitcnt lgkmcnt(4)
	v_mfma_f32_16x16x32_f16 v[12:15], v[78:81], v[170:173], v[12:15]
	v_mfma_f32_16x16x32_f16 v[8:11], v[94:97], v[170:173], v[8:11]
	s_waitcnt lgkmcnt(3)
	v_mfma_f32_16x16x32_f16 v[62:65], v[86:89], v[126:129], v[62:65]
	v_mfma_f32_16x16x32_f16 v[58:61], v[102:105], v[126:129], v[58:61]
	s_waitcnt lgkmcnt(2)
	v_mfma_f32_16x16x32_f16 v[46:49], v[86:89], v[134:137], v[46:49]
	v_mfma_f32_16x16x32_f16 v[42:45], v[102:105], v[134:137], v[42:45]
	s_waitcnt lgkmcnt(1)
	v_mfma_f32_16x16x32_f16 v[28:31], v[86:89], v[158:161], v[28:31]
	v_mfma_f32_16x16x32_f16 v[24:27], v[102:105], v[158:161], v[24:27]
	s_waitcnt lgkmcnt(0)
	v_mfma_f32_16x16x32_f16 v[12:15], v[86:89], v[174:177], v[12:15]
	v_mfma_f32_16x16x32_f16 v[8:11], v[102:105], v[174:177], v[8:11]
	s_setprio 0
	s_barrier
	s_add_u32 s14, s22, 0x40080
	s_addc_u32 s15, s23, 0
	s_add_i32 s22, s24, s13
	v_lshl_add_u64 v[78:79], s[14:15], 0, v[32:33]
	s_mov_b32 m0, s22
	s_nop 0
	global_load_lds_dwordx4 v[78:79], off
	v_lshl_add_u64 v[78:79], s[14:15], 0, v[198:199]
	s_add_i32 m0, s22, 0x2000
	s_nop 0
	global_load_lds_dwordx4 v[78:79], off
	s_waitcnt vmcnt(6)
	s_barrier
	s_setprio 1
	v_mfma_f32_16x16x32_f16 v[54:57], v[182:185], v[122:125], v[54:57]
	v_mfma_f32_16x16x32_f16 v[50:53], v[190:193], v[122:125], v[50:53]
	v_mfma_f32_16x16x32_f16 v[38:41], v[182:185], v[130:133], v[38:41]
	v_mfma_f32_16x16x32_f16 v[34:37], v[190:193], v[130:133], v[34:37]
	v_mfma_f32_16x16x32_f16 v[20:23], v[182:185], v[154:157], v[20:23]
	v_mfma_f32_16x16x32_f16 v[16:19], v[190:193], v[154:157], v[16:19]
	v_mfma_f32_16x16x32_f16 v[4:7], v[182:185], v[170:173], v[4:7]
	v_mfma_f32_16x16x32_f16 v[0:3], v[190:193], v[170:173], v[0:3]
	v_mfma_f32_16x16x32_f16 v[54:57], v[186:189], v[126:129], v[54:57]
	v_mfma_f32_16x16x32_f16 v[50:53], v[194:197], v[126:129], v[50:53]
	v_mfma_f32_16x16x32_f16 v[38:41], v[186:189], v[134:137], v[38:41]
	v_mfma_f32_16x16x32_f16 v[34:37], v[194:197], v[134:137], v[34:37]
	v_mfma_f32_16x16x32_f16 v[20:23], v[186:189], v[158:161], v[20:23]
	v_mfma_f32_16x16x32_f16 v[16:19], v[194:197], v[158:161], v[16:19]
	v_mfma_f32_16x16x32_f16 v[4:7], v[186:189], v[174:177], v[4:7]
	v_mfma_f32_16x16x32_f16 v[0:3], v[194:197], v[174:177], v[0:3]
	s_setprio 0
	s_add_u32 s39, s39, 0x100
	s_addc_u32 s40, s40, 0
	s_cmp_ge_u32 s41, s37
	s_mov_b64 s[14:15], s[20:21]
	s_mov_b32 s22, s41
	s_cbranch_scc0 .Lepib_out_bar
	v_readlane_b32 s51, v251, 36
	s_cmp_gt_u32 s51, 3
	s_cbranch_scc0 .Lepib_out_barx
	s_mov_b32 s50, 1
	s_branch .Lepib_out_exit

.Lepib_out_exit:
.Lpeelx3:
	v_lshl_or_b32 v124, s12, 8, v231
	s_cmp_eq_u32 s10, 0
	s_movk_i32 s12, 0x5000
	s_cselect_b32 s12, 0xe000, s12
	v_readlane_b32 s14, v252, 51
	s_add_u32 s14, s14, s12
	v_readlane_b32 s12, v252, 52
	s_addc_u32 s15, s12, 0
	v_ashrrev_i32_e32 v125, 31, v124
	v_lshl_add_u64 v[86:87], v[124:125], 2, s[14:15]
	global_load_dwordx4 v[94:97], v[86:87], off offset:16
	global_load_dwordx4 v[102:105], v[86:87], off
	global_load_dwordx4 v[78:81], v[86:87], off offset:528
	s_nop 0
	global_load_dwordx4 v[86:89], v[86:87], off offset:512
	v_lshl_add_u32 v130, s10, 8, v229
	v_or_b32_e32 v128, 16, v130
	v_or_b32_e32 v126, 32, v130
	v_or_b32_e32 v122, 48, v130
	s_cmp_eq_u32 s11, 0
	v_ashrrev_i32_e32 v131, 31, v130
	v_ashrrev_i32_e32 v129, 31, v128
	v_ashrrev_i32_e32 v127, 31, v126
	v_ashrrev_i32_e32 v123, 31, v122
	s_cbranch_scc1 .LBB0_1120
	s_add_i32 s96, s11, -1
	s_lshl_b64 s[10:11], s[96:97], 20
	v_readlane_b32 s14, v252, 11
	v_readlane_b32 s15, v252, 12
	s_add_u32 s10, s14, s10
	s_addc_u32 s11, s15, s11
	v_lshlrev_b64 v[132:133], 2, v[124:125]
	v_lshrrev_b32_e32 v134, 5, v220
	v_mul_u32_u24_e32 v134, 48, v134
	s_nop 0
	v_sub_co_u32_e32 v132, vcc, v132, v134
	s_nop 1
	v_subbrev_co_u32_e32 v133, vcc, 0, v133, vcc
	v_lshl_add_u64 v[132:133], s[10:11], 0, v[132:133]
	s_mov_b64 s[10:11], 0x80000
	v_lshlrev_b64 v[204:205], 12, v[130:131]
	v_lshl_add_u64 v[204:205], v[204:205], 0, v[132:133]
	v_lshl_add_u64 v[212:213], v[204:205], 0, s[10:11]
	v_lshlrev_b64 v[206:207], 12, v[128:129]
	v_lshl_add_u64 v[206:207], v[206:207], 0, v[132:133]
	v_lshl_add_u64 v[214:215], v[206:207], 0, s[10:11]
	v_lshlrev_b64 v[208:209], 12, v[126:127]
	v_lshl_add_u64 v[208:209], v[208:209], 0, v[132:133]
	v_lshl_add_u64 v[216:217], v[208:209], 0, s[10:11]
	v_lshlrev_b64 v[210:211], 12, v[122:123]
	v_lshl_add_u64 v[210:211], v[210:211], 0, v[132:133]
	v_lshl_add_u64 v[218:219], v[210:211], 0, s[10:11]
	s_waitcnt vmcnt(0)
	v_pk_mul_f32 v[172:173], v[166:167], v[102:103]
	v_pk_mul_f32 v[174:175], v[168:169], v[104:105]
	v_pk_mul_f32 v[176:177], v[162:163], v[94:95]
	v_pk_mul_f32 v[178:179], v[164:165], v[96:97]
	s_nop 1
	v_permlane32_swap_b32_e32 v172, v176
	v_permlane32_swap_b32_e32 v173, v177
	v_permlane32_swap_b32_e32 v174, v178
	v_permlane32_swap_b32_e32 v175, v179
	s_nop 0
	global_store_dwordx4 v[204:205], v[172:175], off
	global_store_dwordx4 v[204:205], v[176:179], off offset:64
	v_pk_mul_f32 v[180:181], v[146:147], v[86:87]
	v_pk_mul_f32 v[182:183], v[148:149], v[88:89]
	v_pk_mul_f32 v[184:185], v[138:139], v[78:79]
	v_pk_mul_f32 v[186:187], v[140:141], v[80:81]
	s_nop 1
	v_permlane32_swap_b32_e32 v180, v184
	v_permlane32_swap_b32_e32 v181, v185
	v_permlane32_swap_b32_e32 v182, v186
	v_permlane32_swap_b32_e32 v183, v187
	s_nop 0
	global_store_dwordx4 v[204:205], v[180:183], off offset:512
	global_store_dwordx4 v[204:205], v[184:187], off offset:576
	v_pk_mul_f32 v[188:189], v[150:151], v[102:103]
	v_pk_mul_f32 v[190:191], v[152:153], v[104:105]
	v_pk_mul_f32 v[192:193], v[142:143], v[94:95]
	v_pk_mul_f32 v[194:195], v[144:145], v[96:97]
	s_nop 1
	v_permlane32_swap_b32_e32 v188, v192
	v_permlane32_swap_b32_e32 v189, v193
	v_permlane32_swap_b32_e32 v190, v194
	v_permlane32_swap_b32_e32 v191, v195
	s_nop 0
	global_store_dwordx4 v[206:207], v[188:191], off
	global_store_dwordx4 v[206:207], v[192:195], off offset:64
	v_pk_mul_f32 v[154:155], v[118:119], v[86:87]
	v_pk_mul_f32 v[156:157], v[120:121], v[88:89]
	v_pk_mul_f32 v[158:159], v[114:115], v[78:79]
	v_pk_mul_f32 v[160:161], v[116:117], v[80:81]
	s_nop 1
	v_permlane32_swap_b32_e32 v154, v158
	v_permlane32_swap_b32_e32 v155, v159
	v_permlane32_swap_b32_e32 v156, v160
	v_permlane32_swap_b32_e32 v157, v161
	s_nop 0
	global_store_dwordx4 v[206:207], v[154:157], off offset:512
	global_store_dwordx4 v[206:207], v[158:161], off offset:576
	v_pk_mul_f32 v[172:173], v[110:111], v[102:103]
	v_pk_mul_f32 v[174:175], v[112:113], v[104:105]
	v_pk_mul_f32 v[176:177], v[106:107], v[94:95]
	v_pk_mul_f32 v[178:179], v[108:109], v[96:97]
	s_nop 1
	v_permlane32_swap_b32_e32 v172, v176
	v_permlane32_swap_b32_e32 v173, v177
	v_permlane32_swap_b32_e32 v174, v178
	v_permlane32_swap_b32_e32 v175, v179
	s_nop 0
	global_store_dwordx4 v[208:209], v[172:175], off
	global_store_dwordx4 v[208:209], v[176:179], off offset:64
	v_pk_mul_f32 v[180:181], v[98:99], v[86:87]
	v_pk_mul_f32 v[182:183], v[100:101], v[88:89]
	v_pk_mul_f32 v[184:185], v[90:91], v[78:79]
	v_pk_mul_f32 v[186:187], v[92:93], v[80:81]
	s_nop 1
	v_permlane32_swap_b32_e32 v180, v184
	v_permlane32_swap_b32_e32 v181, v185
	v_permlane32_swap_b32_e32 v182, v186
	v_permlane32_swap_b32_e32 v183, v187
	s_nop 0
	global_store_dwordx4 v[208:209], v[180:183], off offset:512
	global_store_dwordx4 v[208:209], v[184:187], off offset:576
	v_pk_mul_f32 v[188:189], v[82:83], v[102:103]
	v_pk_mul_f32 v[190:191], v[84:85], v[104:105]
	v_pk_mul_f32 v[192:193], v[74:75], v[94:95]
	v_pk_mul_f32 v[194:195], v[76:77], v[96:97]
	s_nop 1
	v_permlane32_swap_b32_e32 v188, v192
	v_permlane32_swap_b32_e32 v189, v193
	v_permlane32_swap_b32_e32 v190, v194
	v_permlane32_swap_b32_e32 v191, v195
	s_nop 0
	global_store_dwordx4 v[210:211], v[188:191], off
	global_store_dwordx4 v[210:211], v[192:195], off offset:64
	v_pk_mul_f32 v[154:155], v[70:71], v[86:87]
	v_pk_mul_f32 v[156:157], v[72:73], v[88:89]
	v_pk_mul_f32 v[158:159], v[66:67], v[78:79]
	v_pk_mul_f32 v[160:161], v[68:69], v[80:81]
	s_nop 1
	v_permlane32_swap_b32_e32 v154, v158
	v_permlane32_swap_b32_e32 v155, v159
	v_permlane32_swap_b32_e32 v156, v160
	v_permlane32_swap_b32_e32 v157, v161
	s_nop 0
	global_store_dwordx4 v[210:211], v[154:157], off offset:512
	global_store_dwordx4 v[210:211], v[158:161], off offset:576
	v_pk_mul_f32 v[172:173], v[62:63], v[102:103]
	v_pk_mul_f32 v[174:175], v[64:65], v[104:105]
	v_pk_mul_f32 v[176:177], v[58:59], v[94:95]
	v_pk_mul_f32 v[178:179], v[60:61], v[96:97]
	s_nop 1
	v_permlane32_swap_b32_e32 v172, v176
	v_permlane32_swap_b32_e32 v173, v177
	v_permlane32_swap_b32_e32 v174, v178
	v_permlane32_swap_b32_e32 v175, v179
	s_nop 0
	global_store_dwordx4 v[212:213], v[172:175], off
	global_store_dwordx4 v[212:213], v[176:179], off offset:64
	v_pk_mul_f32 v[180:181], v[54:55], v[86:87]
	v_pk_mul_f32 v[182:183], v[56:57], v[88:89]
	v_pk_mul_f32 v[184:185], v[50:51], v[78:79]
	v_pk_mul_f32 v[186:187], v[52:53], v[80:81]
	s_nop 1
	v_permlane32_swap_b32_e32 v180, v184
	v_permlane32_swap_b32_e32 v181, v185
	v_permlane32_swap_b32_e32 v182, v186
	v_permlane32_swap_b32_e32 v183, v187
	s_nop 0
	global_store_dwordx4 v[212:213], v[180:183], off offset:512
	global_store_dwordx4 v[212:213], v[184:187], off offset:576
	v_pk_mul_f32 v[188:189], v[46:47], v[102:103]
	v_pk_mul_f32 v[190:191], v[48:49], v[104:105]
	v_pk_mul_f32 v[192:193], v[42:43], v[94:95]
	v_pk_mul_f32 v[194:195], v[44:45], v[96:97]
	s_nop 1
	v_permlane32_swap_b32_e32 v188, v192
	v_permlane32_swap_b32_e32 v189, v193
	v_permlane32_swap_b32_e32 v190, v194
	v_permlane32_swap_b32_e32 v191, v195
	s_nop 0
	global_store_dwordx4 v[214:215], v[188:191], off
	global_store_dwordx4 v[214:215], v[192:195], off offset:64
	v_pk_mul_f32 v[154:155], v[38:39], v[86:87]
	v_pk_mul_f32 v[156:157], v[40:41], v[88:89]
	v_pk_mul_f32 v[158:159], v[34:35], v[78:79]
	v_pk_mul_f32 v[160:161], v[36:37], v[80:81]
	s_nop 1
	v_permlane32_swap_b32_e32 v154, v158
	v_permlane32_swap_b32_e32 v155, v159
	v_permlane32_swap_b32_e32 v156, v160
	v_permlane32_swap_b32_e32 v157, v161
	s_nop 0
	global_store_dwordx4 v[214:215], v[154:157], off offset:512
	global_store_dwordx4 v[214:215], v[158:161], off offset:576
	v_pk_mul_f32 v[172:173], v[28:29], v[102:103]
	v_pk_mul_f32 v[174:175], v[30:31], v[104:105]
	v_pk_mul_f32 v[176:177], v[24:25], v[94:95]
	v_pk_mul_f32 v[178:179], v[26:27], v[96:97]
	s_nop 1
	v_permlane32_swap_b32_e32 v172, v176
	v_permlane32_swap_b32_e32 v173, v177
	v_permlane32_swap_b32_e32 v174, v178
	v_permlane32_swap_b32_e32 v175, v179
	s_nop 0
	global_store_dwordx4 v[216:217], v[172:175], off
	global_store_dwordx4 v[216:217], v[176:179], off offset:64
	v_pk_mul_f32 v[180:181], v[20:21], v[86:87]
	v_pk_mul_f32 v[182:183], v[22:23], v[88:89]
	v_pk_mul_f32 v[184:185], v[16:17], v[78:79]
	v_pk_mul_f32 v[186:187], v[18:19], v[80:81]
	s_nop 1
	v_permlane32_swap_b32_e32 v180, v184
	v_permlane32_swap_b32_e32 v181, v185
	v_permlane32_swap_b32_e32 v182, v186
	v_permlane32_swap_b32_e32 v183, v187
	s_nop 0
	global_store_dwordx4 v[216:217], v[180:183], off offset:512
	global_store_dwordx4 v[216:217], v[184:187], off offset:576
	v_pk_mul_f32 v[188:189], v[12:13], v[102:103]
	v_pk_mul_f32 v[190:191], v[14:15], v[104:105]
	v_pk_mul_f32 v[192:193], v[8:9], v[94:95]
	v_pk_mul_f32 v[194:195], v[10:11], v[96:97]
	s_nop 1
	v_permlane32_swap_b32_e32 v188, v192
	v_permlane32_swap_b32_e32 v189, v193
	v_permlane32_swap_b32_e32 v190, v194
	v_permlane32_swap_b32_e32 v191, v195
	s_nop 0
	global_store_dwordx4 v[218:219], v[188:191], off
	global_store_dwordx4 v[218:219], v[192:195], off offset:64
	v_pk_mul_f32 v[154:155], v[4:5], v[86:87]
	v_pk_mul_f32 v[156:157], v[6:7], v[88:89]
	v_pk_mul_f32 v[158:159], v[0:1], v[78:79]
	v_pk_mul_f32 v[160:161], v[2:3], v[80:81]
	s_nop 1
	v_permlane32_swap_b32_e32 v154, v158
	v_permlane32_swap_b32_e32 v155, v159
	v_permlane32_swap_b32_e32 v156, v160
	v_permlane32_swap_b32_e32 v157, v161
	s_nop 0
	global_store_dwordx4 v[218:219], v[154:157], off offset:512
	global_store_dwordx4 v[218:219], v[158:161], off offset:576
	s_cbranch_execnz .LBB0_1104
	s_branch .LBB0_1103

.LBB0_1276:
	s_add_u32 s16, s14, 0x100
	s_addc_u32 s17, s15, 0
	s_add_i32 s39, 0, 0x10000
	v_add_u32_e32 v152, s39, v137
	ds_read_b128 v[140:143], v152
	ds_read_b128 v[148:151], v152 offset:2048
	ds_read_b128 v[144:147], v152 offset:1024
	ds_read_b128 v[152:155], v152 offset:3072
	s_cmp_eq_u32 s38, 12
	s_cselect_b32 s21, s11, s17
	s_cselect_b32 s20, s10, s16
	s_cselect_b32 s19, s13, s37
	s_cselect_b32 s18, s12, s3
	v_lshl_add_u64 v[188:189], s[14:15], 0, v[132:133]
	s_add_i32 m0, s9, 0xc000
	ds_read_b128 v[156:159], v139
	ds_read_b128 v[164:167], v139 offset:2048
	ds_read_b128 v[172:175], v139 offset:4096
	ds_read_b128 v[180:183], v139 offset:6144
	ds_read_b128 v[160:163], v139 offset:1024
	ds_read_b128 v[168:171], v139 offset:3072
	ds_read_b128 v[176:179], v139 offset:5120
	ds_read_b128 v[184:187], v139 offset:7168
	global_load_lds_dwordx4 v[188:189], off
	v_lshl_add_u64 v[188:189], s[14:15], 0, v[134:135]
	s_add_i32 m0, s9, 0xe000
	s_nop 0
	global_load_lds_dwordx4 v[188:189], off
	s_waitcnt lgkmcnt(8)
	s_barrier
	s_waitcnt lgkmcnt(7)
	s_setprio 1
	v_mfma_f32_16x16x32_f16 v[126:129], v[140:143], v[156:159], v[126:129]
	v_mfma_f32_16x16x32_f16 v[122:125], v[148:151], v[156:159], v[122:125]
	s_waitcnt lgkmcnt(6)
	v_mfma_f32_16x16x32_f16 v[110:113], v[140:143], v[164:167], v[110:113]
	v_mfma_f32_16x16x32_f16 v[106:109], v[148:151], v[164:167], v[106:109]
	s_waitcnt lgkmcnt(5)
	v_mfma_f32_16x16x32_f16 v[94:97], v[140:143], v[172:175], v[94:97]
	v_mfma_f32_16x16x32_f16 v[90:93], v[148:151], v[172:175], v[90:93]
	s_waitcnt lgkmcnt(4)
	v_mfma_f32_16x16x32_f16 v[78:81], v[140:143], v[180:183], v[78:81]
	v_mfma_f32_16x16x32_f16 v[74:77], v[148:151], v[180:183], v[74:77]
	s_waitcnt lgkmcnt(3)
	v_mfma_f32_16x16x32_f16 v[126:129], v[144:147], v[160:163], v[126:129]
	v_mfma_f32_16x16x32_f16 v[122:125], v[152:155], v[160:163], v[122:125]
	s_waitcnt lgkmcnt(2)
	v_mfma_f32_16x16x32_f16 v[110:113], v[144:147], v[168:171], v[110:113]
	v_mfma_f32_16x16x32_f16 v[106:109], v[152:155], v[168:171], v[106:109]
	s_waitcnt lgkmcnt(1)
	v_mfma_f32_16x16x32_f16 v[94:97], v[144:147], v[176:179], v[94:97]
	v_mfma_f32_16x16x32_f16 v[90:93], v[152:155], v[176:179], v[90:93]
	s_waitcnt lgkmcnt(0)
	v_mfma_f32_16x16x32_f16 v[78:81], v[144:147], v[184:187], v[78:81]
	v_mfma_f32_16x16x32_f16 v[74:77], v[152:155], v[184:187], v[74:77]
	s_setprio 0
	s_barrier
	s_add_i32 s40, 0, 0x14000
	s_add_i32 s14, s39, s26
	v_add_u32_e32 v200, s40, v137
	v_lshl_add_u64 v[204:205], s[18:19], 0, v[32:33]
	s_mov_b32 m0, s14
	ds_read_b128 v[188:191], v200
	ds_read_b128 v[196:199], v200 offset:2048
	ds_read_b128 v[192:195], v200 offset:1024
	ds_read_b128 v[200:203], v200 offset:3072
	global_load_lds_dwordx4 v[204:205], off
	v_lshl_add_u64 v[206:207], s[18:19], 0, v[130:131]
	s_add_i32 m0, s14, 0x2000
	s_nop 0
	global_load_lds_dwordx4 v[206:207], off
	s_barrier
	s_waitcnt lgkmcnt(2)
	s_setprio 1
	v_mfma_f32_16x16x32_f16 v[118:121], v[188:191], v[156:159], v[118:121]
	v_mfma_f32_16x16x32_f16 v[114:117], v[196:199], v[156:159], v[114:117]
	v_mfma_f32_16x16x32_f16 v[102:105], v[188:191], v[164:167], v[102:105]
	v_mfma_f32_16x16x32_f16 v[98:101], v[196:199], v[164:167], v[98:101]
	v_mfma_f32_16x16x32_f16 v[86:89], v[188:191], v[172:175], v[86:89]
	v_mfma_f32_16x16x32_f16 v[82:85], v[196:199], v[172:175], v[82:85]
	v_mfma_f32_16x16x32_f16 v[70:73], v[188:191], v[180:183], v[70:73]
	v_mfma_f32_16x16x32_f16 v[66:69], v[196:199], v[180:183], v[66:69]
	s_waitcnt lgkmcnt(0)
	v_mfma_f32_16x16x32_f16 v[118:121], v[192:195], v[160:163], v[118:121]
	v_mfma_f32_16x16x32_f16 v[114:117], v[200:203], v[160:163], v[114:117]
	v_mfma_f32_16x16x32_f16 v[102:105], v[192:195], v[168:171], v[102:105]
	v_mfma_f32_16x16x32_f16 v[98:101], v[200:203], v[168:171], v[98:101]
	v_mfma_f32_16x16x32_f16 v[86:89], v[192:195], v[176:179], v[86:89]
	v_mfma_f32_16x16x32_f16 v[82:85], v[200:203], v[176:179], v[82:85]
	v_mfma_f32_16x16x32_f16 v[70:73], v[192:195], v[184:187], v[70:73]
	v_mfma_f32_16x16x32_f16 v[66:69], v[200:203], v[184:187], v[66:69]
	s_setprio 0
	s_mov_b32 m0, s9
	v_lshl_add_u64 v[208:209], s[20:21], 0, v[32:33]
	s_barrier
	ds_read_b128 v[156:159], v139 offset:16384
	ds_read_b128 v[164:167], v139 offset:18432
	ds_read_b128 v[172:175], v139 offset:20480
	ds_read_b128 v[180:183], v139 offset:22528
	ds_read_b128 v[160:163], v139 offset:17408
	ds_read_b128 v[168:171], v139 offset:19456
	ds_read_b128 v[176:179], v139 offset:21504
	ds_read_b128 v[184:187], v139 offset:23552
	global_load_lds_dwordx4 v[208:209], off
	v_lshl_add_u64 v[210:211], s[20:21], 0, v[130:131]
	s_mov_b32 m0, s27
	s_nop 0
	global_load_lds_dwordx4 v[210:211], off
	s_barrier
	s_waitcnt lgkmcnt(7)
	s_setprio 1
	v_mfma_f32_16x16x32_f16 v[62:65], v[140:143], v[156:159], v[62:65]
	v_mfma_f32_16x16x32_f16 v[58:61], v[148:151], v[156:159], v[58:61]
	s_waitcnt lgkmcnt(6)
	v_mfma_f32_16x16x32_f16 v[46:49], v[140:143], v[164:167], v[46:49]
	v_mfma_f32_16x16x32_f16 v[42:45], v[148:151], v[164:167], v[42:45]
	s_waitcnt lgkmcnt(5)
	v_mfma_f32_16x16x32_f16 v[28:31], v[140:143], v[172:175], v[28:31]
	v_mfma_f32_16x16x32_f16 v[24:27], v[148:151], v[172:175], v[24:27]
	s_waitcnt lgkmcnt(4)
	v_mfma_f32_16x16x32_f16 v[12:15], v[140:143], v[180:183], v[12:15]
	v_mfma_f32_16x16x32_f16 v[8:11], v[148:151], v[180:183], v[8:11]
	s_waitcnt lgkmcnt(3)
	v_mfma_f32_16x16x32_f16 v[62:65], v[144:147], v[160:163], v[62:65]
	v_mfma_f32_16x16x32_f16 v[58:61], v[152:155], v[160:163], v[58:61]
	s_waitcnt lgkmcnt(2)
	v_mfma_f32_16x16x32_f16 v[46:49], v[144:147], v[168:171], v[46:49]
	v_mfma_f32_16x16x32_f16 v[42:45], v[152:155], v[168:171], v[42:45]
	s_waitcnt lgkmcnt(1)
	v_mfma_f32_16x16x32_f16 v[28:31], v[144:147], v[176:179], v[28:31]
	v_mfma_f32_16x16x32_f16 v[24:27], v[152:155], v[176:179], v[24:27]
	s_waitcnt lgkmcnt(0)
	v_mfma_f32_16x16x32_f16 v[12:15], v[144:147], v[184:187], v[12:15]
	v_mfma_f32_16x16x32_f16 v[8:11], v[152:155], v[184:187], v[8:11]
	s_setprio 0
	s_barrier
	s_add_u32 s14, s18, 0x40000
	s_addc_u32 s15, s19, 0
	s_add_i32 s39, s40, s26
	v_lshl_add_u64 v[140:141], s[14:15], 0, v[32:33]
	s_mov_b32 m0, s39
	s_nop 0
	global_load_lds_dwordx4 v[140:141], off
	v_lshl_add_u64 v[140:141], s[14:15], 0, v[130:131]
	s_add_i32 m0, s39, 0x2000
	s_nop 0
	global_load_lds_dwordx4 v[140:141], off
	s_waitcnt vmcnt(6)
	s_barrier
	s_setprio 1
	v_mfma_f32_16x16x32_f16 v[54:57], v[188:191], v[156:159], v[54:57]
	v_mfma_f32_16x16x32_f16 v[50:53], v[196:199], v[156:159], v[50:53]
	v_mfma_f32_16x16x32_f16 v[38:41], v[188:191], v[164:167], v[38:41]
	v_mfma_f32_16x16x32_f16 v[34:37], v[196:199], v[164:167], v[34:37]
	v_mfma_f32_16x16x32_f16 v[20:23], v[188:191], v[172:175], v[20:23]
	v_mfma_f32_16x16x32_f16 v[16:19], v[196:199], v[172:175], v[16:19]
	v_mfma_f32_16x16x32_f16 v[4:7], v[188:191], v[180:183], v[4:7]
	v_mfma_f32_16x16x32_f16 v[0:3], v[196:199], v[180:183], v[0:3]
	v_mfma_f32_16x16x32_f16 v[54:57], v[192:195], v[160:163], v[54:57]
	v_mfma_f32_16x16x32_f16 v[50:53], v[200:203], v[160:163], v[50:53]
	v_mfma_f32_16x16x32_f16 v[38:41], v[192:195], v[168:171], v[38:41]
	v_mfma_f32_16x16x32_f16 v[34:37], v[200:203], v[168:171], v[34:37]
	v_mfma_f32_16x16x32_f16 v[20:23], v[192:195], v[176:179], v[20:23]
	v_mfma_f32_16x16x32_f16 v[16:19], v[200:203], v[176:179], v[16:19]
	v_mfma_f32_16x16x32_f16 v[4:7], v[192:195], v[184:187], v[4:7]
	v_mfma_f32_16x16x32_f16 v[0:3], v[200:203], v[184:187], v[0:3]
	s_setprio 0
	s_add_i32 s39, 0, 0x18000
	v_add_u32_e32 v152, s39, v137
	s_barrier
	ds_read_b128 v[140:143], v152
	ds_read_b128 v[148:151], v152 offset:2048
	ds_read_b128 v[144:147], v152 offset:1024
	ds_read_b128 v[152:155], v152 offset:3072
	s_add_u32 s14, s20, 0x40000
	s_addc_u32 s15, s21, 0
	s_mov_b32 m0, s28
	v_lshl_add_u64 v[188:189], s[14:15], 0, v[32:33]
	ds_read_b128 v[156:159], v139 offset:32768
	ds_read_b128 v[164:167], v139 offset:34816
	ds_read_b128 v[172:175], v139 offset:36864
	ds_read_b128 v[180:183], v139 offset:38912
	ds_read_b128 v[160:163], v139 offset:33792
	ds_read_b128 v[168:171], v139 offset:35840
	ds_read_b128 v[176:179], v139 offset:37888
	ds_read_b128 v[184:187], v139 offset:39936
	global_load_lds_dwordx4 v[188:189], off
	v_lshl_add_u64 v[188:189], s[14:15], 0, v[130:131]
	s_mov_b32 m0, s29
	s_nop 0
	global_load_lds_dwordx4 v[188:189], off
	s_waitcnt lgkmcnt(8)
	s_barrier
	s_waitcnt lgkmcnt(7)
	s_setprio 1
	v_mfma_f32_16x16x32_f16 v[126:129], v[140:143], v[156:159], v[126:129]
	v_mfma_f32_16x16x32_f16 v[122:125], v[148:151], v[156:159], v[122:125]
	s_waitcnt lgkmcnt(6)
	v_mfma_f32_16x16x32_f16 v[110:113], v[140:143], v[164:167], v[110:113]
	v_mfma_f32_16x16x32_f16 v[106:109], v[148:151], v[164:167], v[106:109]
	s_waitcnt lgkmcnt(5)
	v_mfma_f32_16x16x32_f16 v[94:97], v[140:143], v[172:175], v[94:97]
	v_mfma_f32_16x16x32_f16 v[90:93], v[148:151], v[172:175], v[90:93]
	s_waitcnt lgkmcnt(4)
	v_mfma_f32_16x16x32_f16 v[78:81], v[140:143], v[180:183], v[78:81]
	v_mfma_f32_16x16x32_f16 v[74:77], v[148:151], v[180:183], v[74:77]
	s_waitcnt lgkmcnt(3)
	v_mfma_f32_16x16x32_f16 v[126:129], v[144:147], v[160:163], v[126:129]
	v_mfma_f32_16x16x32_f16 v[122:125], v[152:155], v[160:163], v[122:125]
	s_waitcnt lgkmcnt(2)
	v_mfma_f32_16x16x32_f16 v[110:113], v[144:147], v[168:171], v[110:113]
	v_mfma_f32_16x16x32_f16 v[106:109], v[152:155], v[168:171], v[106:109]
	s_waitcnt lgkmcnt(1)
	v_mfma_f32_16x16x32_f16 v[94:97], v[144:147], v[176:179], v[94:97]
	v_mfma_f32_16x16x32_f16 v[90:93], v[152:155], v[176:179], v[90:93]
	s_waitcnt lgkmcnt(0)
	v_mfma_f32_16x16x32_f16 v[78:81], v[144:147], v[184:187], v[78:81]
	v_mfma_f32_16x16x32_f16 v[74:77], v[152:155], v[184:187], v[74:77]
	s_setprio 0
	s_barrier
	s_add_i32 s20, 0, 0x1c000
	s_add_i32 s14, s39, s26
	v_add_u32_e32 v200, s20, v137
	v_lshl_add_u64 v[204:205], v[204:205], 0, s[84:85]
	s_mov_b32 m0, s14
	ds_read_b128 v[188:191], v200
	ds_read_b128 v[196:199], v200 offset:2048
	ds_read_b128 v[192:195], v200 offset:1024
	ds_read_b128 v[200:203], v200 offset:3072
	global_load_lds_dwordx4 v[204:205], off
	v_lshl_add_u64 v[204:205], v[206:207], 0, s[84:85]
	s_add_i32 m0, s14, 0x2000
	s_nop 0
	global_load_lds_dwordx4 v[204:205], off
	s_barrier
	s_waitcnt lgkmcnt(2)
	s_setprio 1
	v_mfma_f32_16x16x32_f16 v[118:121], v[188:191], v[156:159], v[118:121]
	v_mfma_f32_16x16x32_f16 v[114:117], v[196:199], v[156:159], v[114:117]
	v_mfma_f32_16x16x32_f16 v[102:105], v[188:191], v[164:167], v[102:105]
	v_mfma_f32_16x16x32_f16 v[98:101], v[196:199], v[164:167], v[98:101]
	v_mfma_f32_16x16x32_f16 v[86:89], v[188:191], v[172:175], v[86:89]
	v_mfma_f32_16x16x32_f16 v[82:85], v[196:199], v[172:175], v[82:85]
	v_mfma_f32_16x16x32_f16 v[70:73], v[188:191], v[180:183], v[70:73]
	v_mfma_f32_16x16x32_f16 v[66:69], v[196:199], v[180:183], v[66:69]
	s_waitcnt lgkmcnt(0)
	v_mfma_f32_16x16x32_f16 v[118:121], v[192:195], v[160:163], v[118:121]
	v_mfma_f32_16x16x32_f16 v[114:117], v[200:203], v[160:163], v[114:117]
	v_mfma_f32_16x16x32_f16 v[102:105], v[192:195], v[168:171], v[102:105]
	v_mfma_f32_16x16x32_f16 v[98:101], v[200:203], v[168:171], v[98:101]
	v_mfma_f32_16x16x32_f16 v[86:89], v[192:195], v[176:179], v[86:89]
	v_mfma_f32_16x16x32_f16 v[82:85], v[200:203], v[176:179], v[82:85]
	v_mfma_f32_16x16x32_f16 v[70:73], v[192:195], v[184:187], v[70:73]
	v_mfma_f32_16x16x32_f16 v[66:69], v[200:203], v[184:187], v[66:69]
	s_setprio 0
	s_mov_b32 m0, s30
	v_lshl_add_u64 v[204:205], v[208:209], 0, s[84:85]
	s_barrier
	ds_read_b128 v[156:159], v139 offset:49152
	ds_read_b128 v[164:167], v139 offset:51200
	ds_read_b128 v[172:175], v139 offset:53248
	ds_read_b128 v[180:183], v139 offset:55296
	ds_read_b128 v[160:163], v139 offset:50176
	ds_read_b128 v[168:171], v139 offset:52224
	ds_read_b128 v[176:179], v139 offset:54272
	ds_read_b128 v[184:187], v139 offset:56320
	global_load_lds_dwordx4 v[204:205], off
	v_lshl_add_u64 v[204:205], v[210:211], 0, s[84:85]
	s_mov_b32 m0, s31
	s_nop 0
	global_load_lds_dwordx4 v[204:205], off
	s_barrier
	s_waitcnt lgkmcnt(7)
	s_setprio 1
	v_mfma_f32_16x16x32_f16 v[62:65], v[140:143], v[156:159], v[62:65]
	v_mfma_f32_16x16x32_f16 v[58:61], v[148:151], v[156:159], v[58:61]
	s_waitcnt lgkmcnt(6)
	v_mfma_f32_16x16x32_f16 v[46:49], v[140:143], v[164:167], v[46:49]
	v_mfma_f32_16x16x32_f16 v[42:45], v[148:151], v[164:167], v[42:45]
	s_waitcnt lgkmcnt(5)
	v_mfma_f32_16x16x32_f16 v[28:31], v[140:143], v[172:175], v[28:31]
	v_mfma_f32_16x16x32_f16 v[24:27], v[148:151], v[172:175], v[24:27]
	s_waitcnt lgkmcnt(4)
	v_mfma_f32_16x16x32_f16 v[12:15], v[140:143], v[180:183], v[12:15]
	v_mfma_f32_16x16x32_f16 v[8:11], v[148:151], v[180:183], v[8:11]
	s_waitcnt lgkmcnt(3)
	v_mfma_f32_16x16x32_f16 v[62:65], v[144:147], v[160:163], v[62:65]
	v_mfma_f32_16x16x32_f16 v[58:61], v[152:155], v[160:163], v[58:61]
	s_waitcnt lgkmcnt(2)
	v_mfma_f32_16x16x32_f16 v[46:49], v[144:147], v[168:171], v[46:49]
	v_mfma_f32_16x16x32_f16 v[42:45], v[152:155], v[168:171], v[42:45]
	s_waitcnt lgkmcnt(1)
	v_mfma_f32_16x16x32_f16 v[28:31], v[144:147], v[176:179], v[28:31]
	v_mfma_f32_16x16x32_f16 v[24:27], v[152:155], v[176:179], v[24:27]
	s_waitcnt lgkmcnt(0)
	v_mfma_f32_16x16x32_f16 v[12:15], v[144:147], v[184:187], v[12:15]
	v_mfma_f32_16x16x32_f16 v[8:11], v[152:155], v[184:187], v[8:11]
	s_setprio 0
	s_barrier
	s_add_u32 s14, s18, 0x40080
	s_addc_u32 s15, s19, 0
	s_add_i32 s18, s20, s26
	v_lshl_add_u64 v[140:141], s[14:15], 0, v[32:33]
	s_mov_b32 m0, s18
	s_nop 0
	global_load_lds_dwordx4 v[140:141], off
	v_lshl_add_u64 v[140:141], s[14:15], 0, v[130:131]
	s_add_i32 m0, s18, 0x2000
	s_nop 0
	global_load_lds_dwordx4 v[140:141], off
	s_waitcnt vmcnt(6)
	s_barrier
	s_setprio 1
	v_mfma_f32_16x16x32_f16 v[54:57], v[188:191], v[156:159], v[54:57]
	v_mfma_f32_16x16x32_f16 v[50:53], v[196:199], v[156:159], v[50:53]
	v_mfma_f32_16x16x32_f16 v[38:41], v[188:191], v[164:167], v[38:41]
	v_mfma_f32_16x16x32_f16 v[34:37], v[196:199], v[164:167], v[34:37]
	v_mfma_f32_16x16x32_f16 v[20:23], v[188:191], v[172:175], v[20:23]
	v_mfma_f32_16x16x32_f16 v[16:19], v[196:199], v[172:175], v[16:19]
	v_mfma_f32_16x16x32_f16 v[4:7], v[188:191], v[180:183], v[4:7]
	v_mfma_f32_16x16x32_f16 v[0:3], v[196:199], v[180:183], v[0:3]
	v_mfma_f32_16x16x32_f16 v[54:57], v[192:195], v[160:163], v[54:57]
	v_mfma_f32_16x16x32_f16 v[50:53], v[200:203], v[160:163], v[50:53]
	v_mfma_f32_16x16x32_f16 v[38:41], v[192:195], v[168:171], v[38:41]
	v_mfma_f32_16x16x32_f16 v[34:37], v[200:203], v[168:171], v[34:37]
	v_mfma_f32_16x16x32_f16 v[20:23], v[192:195], v[176:179], v[20:23]
	v_mfma_f32_16x16x32_f16 v[16:19], v[200:203], v[176:179], v[16:19]
	v_mfma_f32_16x16x32_f16 v[4:7], v[192:195], v[184:187], v[4:7]
	v_mfma_f32_16x16x32_f16 v[0:3], v[200:203], v[184:187], v[0:3]
	s_setprio 0
	s_add_i32 s38, s38, 2
	s_add_u32 s3, s3, 0x100
	s_addc_u32 s37, s37, 0
	s_cmp_gt_u32 s38, 13
	s_mov_b64 s[14:15], s[16:17]
	s_cbranch_scc0 .Lepib_up_bar
	v_readlane_b32 s51, v251, 36
	s_cmp_gt_u32 s51, 3
	s_cbranch_scc0 .Lepib_up_barx
	s_mov_b32 s50, 1
	s_branch .Lepib_up_exit

.LBB0_1338:
	s_mov_b32 s50, 0
	v_readlane_b32 s18, v255, 47
	s_cmp_eq_u32 s18, 0
	s_cselect_b32 s18, s91, s18
	v_readlane_b32 s0, v253, 15
	v_readlane_b32 s2, v254, 25
	v_readlane_b32 s1, v253, 16
	v_readlane_b32 s3, v254, 26
	s_or_b64 s[0:1], s[0:1], s[2:3]
	s_and_b64 s[0:1], s[0:1], exec
	v_readlane_b32 s2, v251, 36
	s_movk_i32 s0, 0x12c
	s_waitcnt vmcnt(0)
	v_lshl_add_u32 v8, s2, 6, v220
	s_movk_i32 s20, 0x100
	s_cmp_lt_u32 s18, 0x100
	s_cbranch_scc1 .Ldne_n
	s_add_i32 s20, s18, 1

.LBB0_1365:
	s_add_i32 s46, s14, 2
	s_add_u32 s12, s10, 0x100
	s_addc_u32 s13, s11, 0
	s_add_i32 s47, 0, 0x10000
	v_add_u32_e32 v134, s47, v230
	ds_read_b128 v[106:109], v134
	ds_read_b128 v[114:117], v134 offset:2048
	ds_read_b128 v[110:113], v134 offset:1024
	ds_read_b128 v[134:137], v134 offset:3072
	s_cmp_eq_u32 s43, s14
	s_cselect_b32 s14, s8, s44
	s_cselect_b32 s17, s7, s13
	s_cselect_b32 s16, s6, s12
	s_cselect_b32 s15, s9, s45
	v_lshl_add_u64 v[178:179], s[10:11], 0, v[184:185]
	s_add_i32 m0, s24, 0xc000
	ds_read_b128 v[138:141], v232
	ds_read_b128 v[154:157], v232 offset:2048
	ds_read_b128 v[162:165], v232 offset:4096
	ds_read_b128 v[170:173], v232 offset:6144
	ds_read_b128 v[150:153], v232 offset:1024
	ds_read_b128 v[158:161], v232 offset:3072
	ds_read_b128 v[166:169], v232 offset:5120
	ds_read_b128 v[174:177], v232 offset:7168
	global_load_lds_dwordx4 v[178:179], off
	v_lshl_add_u64 v[178:179], s[10:11], 0, v[186:187]
	s_add_i32 m0, s24, 0xe000
	s_nop 0
	global_load_lds_dwordx4 v[178:179], off
	s_waitcnt lgkmcnt(8)
	s_barrier
	s_waitcnt lgkmcnt(7)
	s_setprio 1
	v_mfma_f32_16x16x32_f16 v[146:149], v[106:109], v[138:141], v[146:149]
	v_mfma_f32_16x16x32_f16 v[142:145], v[114:117], v[138:141], v[142:145]
	s_waitcnt lgkmcnt(6)
	v_mfma_f32_16x16x32_f16 v[130:133], v[106:109], v[154:157], v[130:133]
	v_mfma_f32_16x16x32_f16 v[122:125], v[114:117], v[154:157], v[122:125]
	s_waitcnt lgkmcnt(5)
	v_mfma_f32_16x16x32_f16 v[94:97], v[106:109], v[162:165], v[94:97]
	v_mfma_f32_16x16x32_f16 v[90:93], v[114:117], v[162:165], v[90:93]
	s_waitcnt lgkmcnt(4)
	v_mfma_f32_16x16x32_f16 v[78:81], v[106:109], v[170:173], v[78:81]
	v_mfma_f32_16x16x32_f16 v[74:77], v[114:117], v[170:173], v[74:77]
	s_waitcnt lgkmcnt(3)
	v_mfma_f32_16x16x32_f16 v[146:149], v[110:113], v[150:153], v[146:149]
	v_mfma_f32_16x16x32_f16 v[142:145], v[134:137], v[150:153], v[142:145]
	s_waitcnt lgkmcnt(2)
	v_mfma_f32_16x16x32_f16 v[130:133], v[110:113], v[158:161], v[130:133]
	v_mfma_f32_16x16x32_f16 v[122:125], v[134:137], v[158:161], v[122:125]
	s_waitcnt lgkmcnt(1)
	v_mfma_f32_16x16x32_f16 v[94:97], v[110:113], v[166:169], v[94:97]
	v_mfma_f32_16x16x32_f16 v[90:93], v[134:137], v[166:169], v[90:93]
	s_waitcnt lgkmcnt(0)
	v_mfma_f32_16x16x32_f16 v[78:81], v[110:113], v[174:177], v[78:81]
	v_mfma_f32_16x16x32_f16 v[74:77], v[134:137], v[174:177], v[74:77]
	s_setprio 0
	s_barrier
	s_add_i32 s48, 0, 0x14000
	s_add_i32 s10, s47, s23
	v_add_u32_e32 v196, s48, v230
	v_lshl_add_u64 v[200:201], s[14:15], 0, v[32:33]
	s_mov_b32 m0, s10
	ds_read_b128 v[178:181], v196
	ds_read_b128 v[192:195], v196 offset:2048
	ds_read_b128 v[188:191], v196 offset:1024
	ds_read_b128 v[196:199], v196 offset:3072
	global_load_lds_dwordx4 v[200:201], off
	v_lshl_add_u64 v[202:203], s[14:15], 0, v[182:183]
	s_add_i32 m0, s10, 0x2000
	s_nop 0
	global_load_lds_dwordx4 v[202:203], off
	s_barrier
	s_waitcnt lgkmcnt(2)
	s_setprio 1
	v_mfma_f32_16x16x32_f16 v[126:129], v[178:181], v[138:141], v[126:129]
	v_mfma_f32_16x16x32_f16 v[118:121], v[192:195], v[138:141], v[118:121]
	v_mfma_f32_16x16x32_f16 v[102:105], v[178:181], v[154:157], v[102:105]
	v_mfma_f32_16x16x32_f16 v[98:101], v[192:195], v[154:157], v[98:101]
	v_mfma_f32_16x16x32_f16 v[86:89], v[178:181], v[162:165], v[86:89]
	v_mfma_f32_16x16x32_f16 v[82:85], v[192:195], v[162:165], v[82:85]
	v_mfma_f32_16x16x32_f16 v[70:73], v[178:181], v[170:173], v[70:73]
	v_mfma_f32_16x16x32_f16 v[66:69], v[192:195], v[170:173], v[66:69]
	s_waitcnt lgkmcnt(0)
	v_mfma_f32_16x16x32_f16 v[126:129], v[188:191], v[150:153], v[126:129]
	v_mfma_f32_16x16x32_f16 v[118:121], v[196:199], v[150:153], v[118:121]
	v_mfma_f32_16x16x32_f16 v[102:105], v[188:191], v[158:161], v[102:105]
	v_mfma_f32_16x16x32_f16 v[98:101], v[196:199], v[158:161], v[98:101]
	v_mfma_f32_16x16x32_f16 v[86:89], v[188:191], v[166:169], v[86:89]
	v_mfma_f32_16x16x32_f16 v[82:85], v[196:199], v[166:169], v[82:85]
	v_mfma_f32_16x16x32_f16 v[70:73], v[188:191], v[174:177], v[70:73]
	v_mfma_f32_16x16x32_f16 v[66:69], v[196:199], v[174:177], v[66:69]
	s_setprio 0
	s_mov_b32 m0, s24
	v_lshl_add_u64 v[204:205], s[16:17], 0, v[32:33]
	s_barrier
	ds_read_b128 v[138:141], v232 offset:16384
	ds_read_b128 v[154:157], v232 offset:18432
	ds_read_b128 v[162:165], v232 offset:20480
	ds_read_b128 v[170:173], v232 offset:22528
	ds_read_b128 v[150:153], v232 offset:17408
	ds_read_b128 v[158:161], v232 offset:19456
	ds_read_b128 v[166:169], v232 offset:21504
	ds_read_b128 v[174:177], v232 offset:23552
	global_load_lds_dwordx4 v[204:205], off
	v_lshl_add_u64 v[206:207], s[16:17], 0, v[182:183]
	s_mov_b32 m0, s25
	s_nop 0
	global_load_lds_dwordx4 v[206:207], off
	s_barrier
	s_waitcnt lgkmcnt(7)
	s_setprio 1
	v_mfma_f32_16x16x32_f16 v[62:65], v[106:109], v[138:141], v[62:65]
	v_mfma_f32_16x16x32_f16 v[58:61], v[114:117], v[138:141], v[58:61]
	s_waitcnt lgkmcnt(6)
	v_mfma_f32_16x16x32_f16 v[46:49], v[106:109], v[154:157], v[46:49]
	v_mfma_f32_16x16x32_f16 v[42:45], v[114:117], v[154:157], v[42:45]
	s_waitcnt lgkmcnt(5)
	v_mfma_f32_16x16x32_f16 v[28:31], v[106:109], v[162:165], v[28:31]
	v_mfma_f32_16x16x32_f16 v[24:27], v[114:117], v[162:165], v[24:27]
	s_waitcnt lgkmcnt(4)
	v_mfma_f32_16x16x32_f16 v[12:15], v[106:109], v[170:173], v[12:15]
	v_mfma_f32_16x16x32_f16 v[8:11], v[114:117], v[170:173], v[8:11]
	s_waitcnt lgkmcnt(3)
	v_mfma_f32_16x16x32_f16 v[62:65], v[110:113], v[150:153], v[62:65]
	v_mfma_f32_16x16x32_f16 v[58:61], v[134:137], v[150:153], v[58:61]
	s_waitcnt lgkmcnt(2)
	v_mfma_f32_16x16x32_f16 v[46:49], v[110:113], v[158:161], v[46:49]
	v_mfma_f32_16x16x32_f16 v[42:45], v[134:137], v[158:161], v[42:45]
	s_waitcnt lgkmcnt(1)
	v_mfma_f32_16x16x32_f16 v[28:31], v[110:113], v[166:169], v[28:31]
	v_mfma_f32_16x16x32_f16 v[24:27], v[134:137], v[166:169], v[24:27]
	s_waitcnt lgkmcnt(0)
	v_mfma_f32_16x16x32_f16 v[12:15], v[110:113], v[174:177], v[12:15]
	v_mfma_f32_16x16x32_f16 v[8:11], v[134:137], v[174:177], v[8:11]
	s_setprio 0
	s_barrier
	s_add_u32 s10, s14, 0xb0000
	s_addc_u32 s11, s15, 0
	s_add_i32 s47, s48, s23
	v_lshl_add_u64 v[106:107], s[10:11], 0, v[32:33]
	s_mov_b32 m0, s47
	s_nop 0
	global_load_lds_dwordx4 v[106:107], off
	v_lshl_add_u64 v[106:107], s[10:11], 0, v[182:183]
	s_add_i32 m0, s47, 0x2000
	s_nop 0
	global_load_lds_dwordx4 v[106:107], off
	s_waitcnt vmcnt(6)
	s_barrier
	s_setprio 1
	v_mfma_f32_16x16x32_f16 v[54:57], v[178:181], v[138:141], v[54:57]
	v_mfma_f32_16x16x32_f16 v[50:53], v[192:195], v[138:141], v[50:53]
	v_mfma_f32_16x16x32_f16 v[38:41], v[178:181], v[154:157], v[38:41]
	v_mfma_f32_16x16x32_f16 v[34:37], v[192:195], v[154:157], v[34:37]
	v_mfma_f32_16x16x32_f16 v[20:23], v[178:181], v[162:165], v[20:23]
	v_mfma_f32_16x16x32_f16 v[16:19], v[192:195], v[162:165], v[16:19]
	v_mfma_f32_16x16x32_f16 v[4:7], v[178:181], v[170:173], v[4:7]
	v_mfma_f32_16x16x32_f16 v[0:3], v[192:195], v[170:173], v[0:3]
	v_mfma_f32_16x16x32_f16 v[54:57], v[188:191], v[150:153], v[54:57]
	v_mfma_f32_16x16x32_f16 v[50:53], v[196:199], v[150:153], v[50:53]
	v_mfma_f32_16x16x32_f16 v[38:41], v[188:191], v[158:161], v[38:41]
	v_mfma_f32_16x16x32_f16 v[34:37], v[196:199], v[158:161], v[34:37]
	v_mfma_f32_16x16x32_f16 v[20:23], v[188:191], v[166:169], v[20:23]
	v_mfma_f32_16x16x32_f16 v[16:19], v[196:199], v[166:169], v[16:19]
	v_mfma_f32_16x16x32_f16 v[4:7], v[188:191], v[174:177], v[4:7]
	v_mfma_f32_16x16x32_f16 v[0:3], v[196:199], v[174:177], v[0:3]
	s_setprio 0
	s_add_i32 s47, 0, 0x18000
	v_add_u32_e32 v134, s47, v230
	s_barrier
	ds_read_b128 v[106:109], v134
	ds_read_b128 v[114:117], v134 offset:2048
	ds_read_b128 v[110:113], v134 offset:1024
	ds_read_b128 v[134:137], v134 offset:3072
	s_add_u32 s10, s16, 0xb0000
	s_addc_u32 s11, s17, 0
	s_mov_b32 m0, s26
	v_lshl_add_u64 v[178:179], s[10:11], 0, v[32:33]
	ds_read_b128 v[138:141], v232 offset:32768
	ds_read_b128 v[154:157], v232 offset:34816
	ds_read_b128 v[162:165], v232 offset:36864
	ds_read_b128 v[170:173], v232 offset:38912
	ds_read_b128 v[150:153], v232 offset:33792
	ds_read_b128 v[158:161], v232 offset:35840
	ds_read_b128 v[166:169], v232 offset:37888
	ds_read_b128 v[174:177], v232 offset:39936
	global_load_lds_dwordx4 v[178:179], off
	v_lshl_add_u64 v[178:179], s[10:11], 0, v[182:183]
	s_mov_b32 m0, s27
	s_nop 0
	global_load_lds_dwordx4 v[178:179], off
	s_waitcnt lgkmcnt(8)
	s_barrier
	s_waitcnt lgkmcnt(7)
	s_setprio 1
	v_mfma_f32_16x16x32_f16 v[146:149], v[106:109], v[138:141], v[146:149]
	v_mfma_f32_16x16x32_f16 v[142:145], v[114:117], v[138:141], v[142:145]
	s_waitcnt lgkmcnt(6)
	v_mfma_f32_16x16x32_f16 v[130:133], v[106:109], v[154:157], v[130:133]
	v_mfma_f32_16x16x32_f16 v[122:125], v[114:117], v[154:157], v[122:125]
	s_waitcnt lgkmcnt(5)
	v_mfma_f32_16x16x32_f16 v[94:97], v[106:109], v[162:165], v[94:97]
	v_mfma_f32_16x16x32_f16 v[90:93], v[114:117], v[162:165], v[90:93]
	s_waitcnt lgkmcnt(4)
	v_mfma_f32_16x16x32_f16 v[78:81], v[106:109], v[170:173], v[78:81]
	v_mfma_f32_16x16x32_f16 v[74:77], v[114:117], v[170:173], v[74:77]
	s_waitcnt lgkmcnt(3)
	v_mfma_f32_16x16x32_f16 v[146:149], v[110:113], v[150:153], v[146:149]
	v_mfma_f32_16x16x32_f16 v[142:145], v[134:137], v[150:153], v[142:145]
	s_waitcnt lgkmcnt(2)
	v_mfma_f32_16x16x32_f16 v[130:133], v[110:113], v[158:161], v[130:133]
	v_mfma_f32_16x16x32_f16 v[122:125], v[134:137], v[158:161], v[122:125]
	s_waitcnt lgkmcnt(1)
	v_mfma_f32_16x16x32_f16 v[94:97], v[110:113], v[166:169], v[94:97]
	v_mfma_f32_16x16x32_f16 v[90:93], v[134:137], v[166:169], v[90:93]
	s_waitcnt lgkmcnt(0)
	v_mfma_f32_16x16x32_f16 v[78:81], v[110:113], v[174:177], v[78:81]
	v_mfma_f32_16x16x32_f16 v[74:77], v[134:137], v[174:177], v[74:77]
	s_setprio 0
	s_barrier
	s_add_i32 s16, 0, 0x1c000
	s_add_i32 s10, s47, s23
	v_add_u32_e32 v196, s16, v230
	v_lshl_add_u64 v[200:201], v[200:201], 0, s[84:85]
	s_mov_b32 m0, s10
	ds_read_b128 v[178:181], v196
	ds_read_b128 v[192:195], v196 offset:2048
	ds_read_b128 v[188:191], v196 offset:1024
	ds_read_b128 v[196:199], v196 offset:3072
	global_load_lds_dwordx4 v[200:201], off
	v_lshl_add_u64 v[200:201], v[202:203], 0, s[84:85]
	s_add_i32 m0, s10, 0x2000
	s_nop 0
	global_load_lds_dwordx4 v[200:201], off
	s_barrier
	s_waitcnt lgkmcnt(2)
	s_setprio 1
	v_mfma_f32_16x16x32_f16 v[126:129], v[178:181], v[138:141], v[126:129]
	v_mfma_f32_16x16x32_f16 v[118:121], v[192:195], v[138:141], v[118:121]
	v_mfma_f32_16x16x32_f16 v[102:105], v[178:181], v[154:157], v[102:105]
	v_mfma_f32_16x16x32_f16 v[98:101], v[192:195], v[154:157], v[98:101]
	v_mfma_f32_16x16x32_f16 v[86:89], v[178:181], v[162:165], v[86:89]
	v_mfma_f32_16x16x32_f16 v[82:85], v[192:195], v[162:165], v[82:85]
	v_mfma_f32_16x16x32_f16 v[70:73], v[178:181], v[170:173], v[70:73]
	v_mfma_f32_16x16x32_f16 v[66:69], v[192:195], v[170:173], v[66:69]
	s_waitcnt lgkmcnt(0)
	v_mfma_f32_16x16x32_f16 v[126:129], v[188:191], v[150:153], v[126:129]
	v_mfma_f32_16x16x32_f16 v[118:121], v[196:199], v[150:153], v[118:121]
	v_mfma_f32_16x16x32_f16 v[102:105], v[188:191], v[158:161], v[102:105]
	v_mfma_f32_16x16x32_f16 v[98:101], v[196:199], v[158:161], v[98:101]
	v_mfma_f32_16x16x32_f16 v[86:89], v[188:191], v[166:169], v[86:89]
	v_mfma_f32_16x16x32_f16 v[82:85], v[196:199], v[166:169], v[82:85]
	v_mfma_f32_16x16x32_f16 v[70:73], v[188:191], v[174:177], v[70:73]
	v_mfma_f32_16x16x32_f16 v[66:69], v[196:199], v[174:177], v[66:69]
	s_setprio 0
	s_mov_b32 m0, s29
	v_lshl_add_u64 v[200:201], v[204:205], 0, s[84:85]
	s_barrier
	ds_read_b128 v[138:141], v232 offset:49152
	ds_read_b128 v[154:157], v232 offset:51200
	ds_read_b128 v[162:165], v232 offset:53248
	ds_read_b128 v[170:173], v232 offset:55296
	ds_read_b128 v[150:153], v232 offset:50176
	ds_read_b128 v[158:161], v232 offset:52224
	ds_read_b128 v[166:169], v232 offset:54272
	ds_read_b128 v[174:177], v232 offset:56320
	global_load_lds_dwordx4 v[200:201], off
	v_lshl_add_u64 v[200:201], v[206:207], 0, s[84:85]
	s_mov_b32 m0, s30
	s_nop 0
	global_load_lds_dwordx4 v[200:201], off
	s_barrier
	s_waitcnt lgkmcnt(7)
	s_setprio 1
	v_mfma_f32_16x16x32_f16 v[62:65], v[106:109], v[138:141], v[62:65]
	v_mfma_f32_16x16x32_f16 v[58:61], v[114:117], v[138:141], v[58:61]
	s_waitcnt lgkmcnt(6)
	v_mfma_f32_16x16x32_f16 v[46:49], v[106:109], v[154:157], v[46:49]
	v_mfma_f32_16x16x32_f16 v[42:45], v[114:117], v[154:157], v[42:45]
	s_waitcnt lgkmcnt(5)
	v_mfma_f32_16x16x32_f16 v[28:31], v[106:109], v[162:165], v[28:31]
	v_mfma_f32_16x16x32_f16 v[24:27], v[114:117], v[162:165], v[24:27]
	s_waitcnt lgkmcnt(4)
	v_mfma_f32_16x16x32_f16 v[12:15], v[106:109], v[170:173], v[12:15]
	v_mfma_f32_16x16x32_f16 v[8:11], v[114:117], v[170:173], v[8:11]
	s_waitcnt lgkmcnt(3)
	v_mfma_f32_16x16x32_f16 v[62:65], v[110:113], v[150:153], v[62:65]
	v_mfma_f32_16x16x32_f16 v[58:61], v[134:137], v[150:153], v[58:61]
	s_waitcnt lgkmcnt(2)
	v_mfma_f32_16x16x32_f16 v[46:49], v[110:113], v[158:161], v[46:49]
	v_mfma_f32_16x16x32_f16 v[42:45], v[134:137], v[158:161], v[42:45]
	s_waitcnt lgkmcnt(1)
	v_mfma_f32_16x16x32_f16 v[28:31], v[110:113], v[166:169], v[28:31]
	v_mfma_f32_16x16x32_f16 v[24:27], v[134:137], v[166:169], v[24:27]
	s_waitcnt lgkmcnt(0)
	v_mfma_f32_16x16x32_f16 v[12:15], v[110:113], v[174:177], v[12:15]
	v_mfma_f32_16x16x32_f16 v[8:11], v[134:137], v[174:177], v[8:11]
	s_setprio 0
	s_barrier
	s_add_u32 s10, s14, 0xb0080
	s_addc_u32 s11, s15, 0
	s_add_i32 s14, s16, s23
	v_lshl_add_u64 v[106:107], s[10:11], 0, v[32:33]
	s_mov_b32 m0, s14
	s_nop 0
	global_load_lds_dwordx4 v[106:107], off
	v_lshl_add_u64 v[106:107], s[10:11], 0, v[182:183]
	s_add_i32 m0, s14, 0x2000
	s_nop 0
	global_load_lds_dwordx4 v[106:107], off
	s_waitcnt vmcnt(6)
	s_barrier
	s_setprio 1
	v_mfma_f32_16x16x32_f16 v[54:57], v[178:181], v[138:141], v[54:57]
	v_mfma_f32_16x16x32_f16 v[50:53], v[192:195], v[138:141], v[50:53]
	v_mfma_f32_16x16x32_f16 v[38:41], v[178:181], v[154:157], v[38:41]
	v_mfma_f32_16x16x32_f16 v[34:37], v[192:195], v[154:157], v[34:37]
	v_mfma_f32_16x16x32_f16 v[20:23], v[178:181], v[162:165], v[20:23]
	v_mfma_f32_16x16x32_f16 v[16:19], v[192:195], v[162:165], v[16:19]
	v_mfma_f32_16x16x32_f16 v[4:7], v[178:181], v[170:173], v[4:7]
	v_mfma_f32_16x16x32_f16 v[0:3], v[192:195], v[170:173], v[0:3]
	v_mfma_f32_16x16x32_f16 v[54:57], v[188:191], v[150:153], v[54:57]
	v_mfma_f32_16x16x32_f16 v[50:53], v[196:199], v[150:153], v[50:53]
	v_mfma_f32_16x16x32_f16 v[38:41], v[188:191], v[158:161], v[38:41]
	v_mfma_f32_16x16x32_f16 v[34:37], v[196:199], v[158:161], v[34:37]
	v_mfma_f32_16x16x32_f16 v[20:23], v[188:191], v[166:169], v[20:23]
	v_mfma_f32_16x16x32_f16 v[16:19], v[196:199], v[166:169], v[16:19]
	v_mfma_f32_16x16x32_f16 v[4:7], v[188:191], v[174:177], v[4:7]
	v_mfma_f32_16x16x32_f16 v[0:3], v[196:199], v[174:177], v[0:3]
	s_setprio 0
	s_add_u32 s44, s44, 0x100
	s_addc_u32 s45, s45, 0
	s_cmp_ge_u32 s46, s42
	s_mov_b64 s[10:11], s[12:13]
	s_mov_b32 s14, s46
	s_cbranch_scc0 .Lepib_dn_bar
	v_readlane_b32 s51, v251, 36
	s_cmp_gt_u32 s51, 3
	s_cbranch_scc0 .Lepib_dn_barx
	s_mov_b32 s50, 1
	s_branch .Lepib_dn_exit

.Lepib_dn_exit:
.Lpeelx5:
	s_cmp_eq_u32 s40, 0
	s_cselect_b32 s6, 0x9000, 0
	v_lshl_or_b32 v106, s41, 8, v231
	s_add_u32 s6, s31, s6
	s_addc_u32 s7, s34, 0
	v_ashrrev_i32_e32 v107, 31, v106
	v_lshl_add_u64 v[116:117], v[106:107], 2, s[6:7]
	global_load_dwordx4 v[108:111], v[116:117], off offset:16
	global_load_dwordx4 v[112:115], v[116:117], off
	s_cmp_eq_u32 s39, 0
	s_waitcnt vmcnt(0)
	v_pk_mul_f32 v[194:195], v[110:111], 0.5 op_sel_hi:[1,0]
	v_pk_mul_f32 v[198:199], v[114:115], 0.5 op_sel_hi:[1,0]
	v_pk_mul_f32 v[202:203], v[112:113], 0.5 op_sel_hi:[1,0]
	v_pk_mul_f32 v[200:201], v[108:109], 0.5 op_sel_hi:[1,0]
	global_load_dwordx4 v[108:111], v[116:117], off offset:528
	global_load_dwordx4 v[112:115], v[116:117], off offset:512
	s_waitcnt vmcnt(0)
	v_pk_mul_f32 v[188:189], v[110:111], 0.5 op_sel_hi:[1,0]
	v_pk_mul_f32 v[196:197], v[112:113], 0.5 op_sel_hi:[1,0]
	v_lshl_add_u32 v112, s40, 8, v229
	v_pk_mul_f32 v[190:191], v[114:115], 0.5 op_sel_hi:[1,0]
	v_pk_mul_f32 v[192:193], v[108:109], 0.5 op_sel_hi:[1,0]
	v_or_b32_e32 v114, 16, v112
	v_or_b32_e32 v110, 32, v112
	v_or_b32_e32 v108, 48, v112
	v_ashrrev_i32_e32 v113, 31, v112
	v_ashrrev_i32_e32 v115, 31, v114
	v_ashrrev_i32_e32 v111, 31, v110
	v_ashrrev_i32_e32 v109, 31, v108
	s_cbranch_scc1 .LBB0_1368
	s_add_i32 s96, s39, -1
	s_lshl_b64 s[6:7], s[96:97], 20
	v_readlane_b32 s8, v252, 11
	v_readlane_b32 s9, v252, 12
	s_add_u32 s6, s8, s6
	s_addc_u32 s7, s9, s7
	v_lshlrev_b64 v[138:139], 2, v[106:107]
	v_lshrrev_b32_e32 v150, 5, v220
	v_mul_u32_u24_e32 v150, 48, v150
	s_nop 0
	v_sub_co_u32_e32 v138, vcc, v138, v150
	s_nop 1
	v_subbrev_co_u32_e32 v139, vcc, 0, v139, vcc
	v_lshl_add_u64 v[138:139], s[6:7], 0, v[138:139]
	s_mov_b64 s[6:7], 0x80000
	v_lshlrev_b64 v[204:205], 12, v[112:113]
	v_lshl_add_u64 v[204:205], v[204:205], 0, v[138:139]
	v_lshl_add_u64 v[212:213], v[204:205], 0, s[6:7]
	v_lshlrev_b64 v[206:207], 12, v[114:115]
	v_lshl_add_u64 v[206:207], v[206:207], 0, v[138:139]
	v_lshl_add_u64 v[214:215], v[206:207], 0, s[6:7]
	v_lshlrev_b64 v[208:209], 12, v[110:111]
	v_lshl_add_u64 v[208:209], v[208:209], 0, v[138:139]
	v_lshl_add_u64 v[216:217], v[208:209], 0, s[6:7]
	v_lshlrev_b64 v[210:211], 12, v[108:109]
	v_lshl_add_u64 v[210:211], v[210:211], 0, v[138:139]
	v_lshl_add_u64 v[218:219], v[210:211], 0, s[6:7]
	s_waitcnt vmcnt(0)
	v_pk_mul_f32 v[152:153], v[146:147], v[202:203]
	v_pk_mul_f32 v[154:155], v[148:149], v[198:199]
	v_pk_mul_f32 v[156:157], v[142:143], v[200:201]
	v_pk_mul_f32 v[158:159], v[144:145], v[194:195]
	s_nop 1
	v_permlane32_swap_b32_e32 v152, v156
	v_permlane32_swap_b32_e32 v153, v157
	v_permlane32_swap_b32_e32 v154, v158
	v_permlane32_swap_b32_e32 v155, v159
	s_nop 0
	global_store_dwordx4 v[204:205], v[152:155], off
	global_store_dwordx4 v[204:205], v[156:159], off offset:64
	v_pk_mul_f32 v[160:161], v[126:127], v[196:197]
	v_pk_mul_f32 v[162:163], v[128:129], v[190:191]
	v_pk_mul_f32 v[164:165], v[118:119], v[192:193]
	v_pk_mul_f32 v[166:167], v[120:121], v[188:189]
	s_nop 1
	v_permlane32_swap_b32_e32 v160, v164
	v_permlane32_swap_b32_e32 v161, v165
	v_permlane32_swap_b32_e32 v162, v166
	v_permlane32_swap_b32_e32 v163, v167
	s_nop 0
	global_store_dwordx4 v[204:205], v[160:163], off offset:512
	global_store_dwordx4 v[204:205], v[164:167], off offset:576
	v_pk_mul_f32 v[168:169], v[130:131], v[202:203]
	v_pk_mul_f32 v[170:171], v[132:133], v[198:199]
	v_pk_mul_f32 v[172:173], v[122:123], v[200:201]
	v_pk_mul_f32 v[174:175], v[124:125], v[194:195]
	s_nop 1
	v_permlane32_swap_b32_e32 v168, v172
	v_permlane32_swap_b32_e32 v169, v173
	v_permlane32_swap_b32_e32 v170, v174
	v_permlane32_swap_b32_e32 v171, v175
	s_nop 0
	global_store_dwordx4 v[206:207], v[168:171], off
	global_store_dwordx4 v[206:207], v[172:175], off offset:64
	v_pk_mul_f32 v[176:177], v[102:103], v[196:197]
	v_pk_mul_f32 v[178:179], v[104:105], v[190:191]
	v_pk_mul_f32 v[180:181], v[98:99], v[192:193]
	v_pk_mul_f32 v[182:183], v[100:101], v[188:189]
	s_nop 1
	v_permlane32_swap_b32_e32 v176, v180
	v_permlane32_swap_b32_e32 v177, v181
	v_permlane32_swap_b32_e32 v178, v182
	v_permlane32_swap_b32_e32 v179, v183
	s_nop 0
	global_store_dwordx4 v[206:207], v[176:179], off offset:512
	global_store_dwordx4 v[206:207], v[180:183], off offset:576
	v_pk_mul_f32 v[152:153], v[94:95], v[202:203]
	v_pk_mul_f32 v[154:155], v[96:97], v[198:199]
	v_pk_mul_f32 v[156:157], v[90:91], v[200:201]
	v_pk_mul_f32 v[158:159], v[92:93], v[194:195]
	s_nop 1
	v_permlane32_swap_b32_e32 v152, v156
	v_permlane32_swap_b32_e32 v153, v157
	v_permlane32_swap_b32_e32 v154, v158
	v_permlane32_swap_b32_e32 v155, v159
	s_nop 0
	global_store_dwordx4 v[208:209], v[152:155], off
	global_store_dwordx4 v[208:209], v[156:159], off offset:64
	v_pk_mul_f32 v[160:161], v[86:87], v[196:197]
	v_pk_mul_f32 v[162:163], v[88:89], v[190:191]
	v_pk_mul_f32 v[164:165], v[82:83], v[192:193]
	v_pk_mul_f32 v[166:167], v[84:85], v[188:189]
	s_nop 1
	v_permlane32_swap_b32_e32 v160, v164
	v_permlane32_swap_b32_e32 v161, v165
	v_permlane32_swap_b32_e32 v162, v166
	v_permlane32_swap_b32_e32 v163, v167
	s_nop 0
	global_store_dwordx4 v[208:209], v[160:163], off offset:512
	global_store_dwordx4 v[208:209], v[164:167], off offset:576
	v_pk_mul_f32 v[168:169], v[78:79], v[202:203]
	v_pk_mul_f32 v[170:171], v[80:81], v[198:199]
	v_pk_mul_f32 v[172:173], v[74:75], v[200:201]
	v_pk_mul_f32 v[174:175], v[76:77], v[194:195]
	s_nop 1
	v_permlane32_swap_b32_e32 v168, v172
	v_permlane32_swap_b32_e32 v169, v173
	v_permlane32_swap_b32_e32 v170, v174
	v_permlane32_swap_b32_e32 v171, v175
	s_nop 0
	global_store_dwordx4 v[210:211], v[168:171], off
	global_store_dwordx4 v[210:211], v[172:175], off offset:64
	v_pk_mul_f32 v[176:177], v[70:71], v[196:197]
	v_pk_mul_f32 v[178:179], v[72:73], v[190:191]
	v_pk_mul_f32 v[180:181], v[66:67], v[192:193]
	v_pk_mul_f32 v[182:183], v[68:69], v[188:189]
	s_nop 1
	v_permlane32_swap_b32_e32 v176, v180
	v_permlane32_swap_b32_e32 v177, v181
	v_permlane32_swap_b32_e32 v178, v182
	v_permlane32_swap_b32_e32 v179, v183
	s_nop 0
	global_store_dwordx4 v[210:211], v[176:179], off offset:512
	global_store_dwordx4 v[210:211], v[180:183], off offset:576
	v_pk_mul_f32 v[152:153], v[62:63], v[202:203]
	v_pk_mul_f32 v[154:155], v[64:65], v[198:199]
	v_pk_mul_f32 v[156:157], v[58:59], v[200:201]
	v_pk_mul_f32 v[158:159], v[60:61], v[194:195]
	s_nop 1
	v_permlane32_swap_b32_e32 v152, v156
	v_permlane32_swap_b32_e32 v153, v157
	v_permlane32_swap_b32_e32 v154, v158
	v_permlane32_swap_b32_e32 v155, v159
	s_nop 0
	global_store_dwordx4 v[212:213], v[152:155], off
	global_store_dwordx4 v[212:213], v[156:159], off offset:64
	v_pk_mul_f32 v[160:161], v[54:55], v[196:197]
	v_pk_mul_f32 v[162:163], v[56:57], v[190:191]
	v_pk_mul_f32 v[164:165], v[50:51], v[192:193]
	v_pk_mul_f32 v[166:167], v[52:53], v[188:189]
	s_nop 1
	v_permlane32_swap_b32_e32 v160, v164
	v_permlane32_swap_b32_e32 v161, v165
	v_permlane32_swap_b32_e32 v162, v166
	v_permlane32_swap_b32_e32 v163, v167
	s_nop 0
	global_store_dwordx4 v[212:213], v[160:163], off offset:512
	global_store_dwordx4 v[212:213], v[164:167], off offset:576
	v_pk_mul_f32 v[168:169], v[46:47], v[202:203]
	v_pk_mul_f32 v[170:171], v[48:49], v[198:199]
	v_pk_mul_f32 v[172:173], v[42:43], v[200:201]
	v_pk_mul_f32 v[174:175], v[44:45], v[194:195]
	s_nop 1
	v_permlane32_swap_b32_e32 v168, v172
	v_permlane32_swap_b32_e32 v169, v173
	v_permlane32_swap_b32_e32 v170, v174
	v_permlane32_swap_b32_e32 v171, v175
	s_nop 0
	global_store_dwordx4 v[214:215], v[168:171], off
	global_store_dwordx4 v[214:215], v[172:175], off offset:64
	v_pk_mul_f32 v[176:177], v[38:39], v[196:197]
	v_pk_mul_f32 v[178:179], v[40:41], v[190:191]
	v_pk_mul_f32 v[180:181], v[34:35], v[192:193]
	v_pk_mul_f32 v[182:183], v[36:37], v[188:189]
	s_nop 1
	v_permlane32_swap_b32_e32 v176, v180
	v_permlane32_swap_b32_e32 v177, v181
	v_permlane32_swap_b32_e32 v178, v182
	v_permlane32_swap_b32_e32 v179, v183
	s_nop 0
	global_store_dwordx4 v[214:215], v[176:179], off offset:512
	global_store_dwordx4 v[214:215], v[180:183], off offset:576
	v_pk_mul_f32 v[152:153], v[28:29], v[202:203]
	v_pk_mul_f32 v[154:155], v[30:31], v[198:199]
	v_pk_mul_f32 v[156:157], v[24:25], v[200:201]
	v_pk_mul_f32 v[158:159], v[26:27], v[194:195]
	s_nop 1
	v_permlane32_swap_b32_e32 v152, v156
	v_permlane32_swap_b32_e32 v153, v157
	v_permlane32_swap_b32_e32 v154, v158
	v_permlane32_swap_b32_e32 v155, v159
	s_nop 0
	global_store_dwordx4 v[216:217], v[152:155], off
	global_store_dwordx4 v[216:217], v[156:159], off offset:64
	v_pk_mul_f32 v[160:161], v[20:21], v[196:197]
	v_pk_mul_f32 v[162:163], v[22:23], v[190:191]
	v_pk_mul_f32 v[164:165], v[16:17], v[192:193]
	v_pk_mul_f32 v[166:167], v[18:19], v[188:189]
	s_nop 1
	v_permlane32_swap_b32_e32 v160, v164
	v_permlane32_swap_b32_e32 v161, v165
	v_permlane32_swap_b32_e32 v162, v166
	v_permlane32_swap_b32_e32 v163, v167
	s_nop 0
	global_store_dwordx4 v[216:217], v[160:163], off offset:512
	global_store_dwordx4 v[216:217], v[164:167], off offset:576
	v_pk_mul_f32 v[168:169], v[12:13], v[202:203]
	v_pk_mul_f32 v[170:171], v[14:15], v[198:199]
	v_pk_mul_f32 v[172:173], v[8:9], v[200:201]
	v_pk_mul_f32 v[174:175], v[10:11], v[194:195]
	s_nop 1
	v_permlane32_swap_b32_e32 v168, v172
	v_permlane32_swap_b32_e32 v169, v173
	v_permlane32_swap_b32_e32 v170, v174
	v_permlane32_swap_b32_e32 v171, v175
	s_nop 0
	global_store_dwordx4 v[218:219], v[168:171], off
	global_store_dwordx4 v[218:219], v[172:175], off offset:64
	v_pk_mul_f32 v[176:177], v[4:5], v[196:197]
	v_pk_mul_f32 v[178:179], v[6:7], v[190:191]
	v_pk_mul_f32 v[180:181], v[0:1], v[192:193]
	v_pk_mul_f32 v[182:183], v[2:3], v[188:189]
	s_nop 1
	v_permlane32_swap_b32_e32 v176, v180
	v_permlane32_swap_b32_e32 v177, v181
	v_permlane32_swap_b32_e32 v178, v182
	v_permlane32_swap_b32_e32 v179, v183
	s_nop 0
	global_store_dwordx4 v[218:219], v[176:179], off offset:512
	global_store_dwordx4 v[218:219], v[180:183], off offset:576
	s_cbranch_execnz .LBB0_1352
	s_branch .LBB0_1351
